# fused-norm tail: gain/scale/shift vector loads hoisted above the row-statistics exchange (out-GEMM and MLP-down instances), on top of v31
# baseline (speedup 1.0000x reference)
;     __device__ __forceinline__ void fuse_tail(f32x4 (&acc)[2][2][4][2], const float (&ssq)[2][4], const Unit& u, int wr, int wc, int fr, int fq, int mi, int row0, int col0) const {
;     ...
;         if (wid == 0) { unsigned sp = 0u;
;             while ((unsigned)__builtin_amdgcn_readfirstlane((int)__hip_atomic_load(pc, __ATOMIC_RELAXED, __HIP_MEMORY_SCOPE_AGENT)) < want) { __builtin_amdgcn_s_sleep(1); if (++sp > (1u << 18)) break; }
;             __builtin_amdgcn_fence(__ATOMIC_ACQUIRE, "agent"); }
;         asm volatile("s_waitcnt lgkmcnt(0)" ::: "memory"); __builtin_amdgcn_s_barrier(); asm volatile("" ::: "memory");
;         if (lane < 32) { float t = 0.f;
; #pragma unroll
;             for (int k = 0; k < 8; ++k) t += __builtin_bit_cast(float, __hip_atomic_load(slots + k, __ATOMIC_RELAXED, __HIP_MEMORY_SCOPE_AGENT));
;             S[row] = rsqrtf(t * (1.f / D) + 1e-6f); }
;         asm volatile("s_waitcnt lgkmcnt(0)" ::: "memory"); __builtin_amdgcn_s_barrier(); asm volatile("" ::: "memory");
;         if (FUSE == 2) {
;             float* ob = slab + (size_t)row0 * D + col0;
; #pragma unroll
;             for (int bj = 0; bj < 2; ++bj) { const f32x4 G0 = *(const f32x4*)(ng + col0 + bj * HALF), G1 = *(const f32x4*)(ng + col0 + bj * HALF + 4);
; #pragma unroll
;                 for (int ai = 0; ai < 2; ++ai)
; #pragma unroll
;                     for (int m = 0; m < 4; ++m) { const float rstd = S[ai * HALF + wr * 64 + m * 16 + fr];
;                         *(f32x4*)(ob + (size_t)(ai * HALF + m * 16) * D + bj * HALF) = acc[ai][bj][m][0] * rstd * G0; *(f32x4*)(ob + (size_t)(ai * HALF + m * 16) * D + bj * HALF + 4) = acc[ai][bj][m][1] * rstd * G1; } }
;             return;
;         }
;         bf16_t* XN = (bf16_t*)((char*)X + RN_DXN);
;         const float* sh = mods_l + nsh_off + (size_t)mi * MODW + col0;
; #pragma unroll
;         for (int bj = 0; bj < 2; ++bj) { f32x4 GG[2], SS[2];
; #pragma unroll
;             for (int n = 0; n < 2; ++n) { GG[n] = *(const f32x4*)(ng + col0 + bj * HALF + 4 * n) * (*(const f32x4*)(sh + D + bj * HALF + 4 * n) + 1.f); SS[n] = *(const f32x4*)(sh + bj * HALF + 4 * n); }
; #pragma unroll
;             for (int ai = 0; ai < 2; ++ai)
; #pragma unroll
;                 for (int m = 0; m < 4; ++m) { const float rstd = S[ai * HALF + wr * 64 + m * 16 + fr];
.LBB9_1196:
	s_add_u32 s98, s85, s48
	s_addc_u32 s99, s86, s5
	v_lshlrev_b64 v[174:175], 2, v[234:235]
	v_lshl_add_u64 v[176:177], s[98:99], 0, v[174:175]
	v_lshl_add_u64 v[178:179], s[20:21], 0, v[174:175]
	s_mov_b32 s98, s28
	s_mov_b32 s99, 0
	v_lshl_add_u64 v[180:181], v[176:177], 0, s[98:99]
	s_mov_b64 s[98:99], 0x2000
	v_lshl_add_u64 v[182:183], v[176:177], 0, s[98:99]
	global_load_dwordx4 v[150:153], v[178:179], off offset:16
	global_load_dwordx4 v[154:157], v[178:179], off
	global_load_dwordx4 v[158:161], v[180:181], off
	global_load_dwordx4 v[162:165], v[182:183], off offset:16
	global_load_dwordx4 v[166:169], v[176:177], off offset:16
	global_load_dwordx4 v[170:173], v[176:177], off
	s_waitcnt lgkmcnt(0)
	s_barrier
	s_and_saveexec_b64 s[44:45], s[40:41]
	s_cbranch_execz .LBB9_1198
	global_load_dword v4, v[2:3], off sc1
	global_load_dword v5, v[2:3], off offset:4 sc1
	global_load_dword v7, v[2:3], off offset:8 sc1
	global_load_dword v8, v[2:3], off offset:12 sc1
	global_load_dword v9, v[2:3], off offset:16 sc1
	global_load_dword v130, v[2:3], off offset:20 sc1
	global_load_dword v131, v[2:3], off offset:24 sc1
	global_load_dword v132, v[2:3], off offset:28 sc1
	s_mov_b32 s3, 0x800000
	s_waitcnt vmcnt(7)
	v_add_f32_e32 v4, 0, v4
	s_waitcnt vmcnt(6)
	v_add_f32_e32 v4, v4, v5
	s_waitcnt vmcnt(5)
	v_add_f32_e32 v4, v4, v7
	s_waitcnt vmcnt(4)
	v_add_f32_e32 v4, v4, v8
	s_waitcnt vmcnt(3)
	v_add_f32_e32 v4, v4, v9
	s_waitcnt vmcnt(2)
	v_add_f32_e32 v4, v4, v130
	s_waitcnt vmcnt(1)
	v_add_f32_e32 v4, v4, v131
	s_waitcnt vmcnt(0)
	v_add_f32_e32 v2, v4, v132
	v_fmamk_f32 v2, v2, 0x3a000000, v238
	v_cmp_gt_f32_e32 vcc, s3, v2
	v_mul_f32_e32 v3, 0x4b800000, v2
	s_nop 0
	v_cndmask_b32_e32 v2, v2, v3, vcc
	v_rsq_f32_e32 v2, v2
	s_nop 0
	v_mul_f32_e32 v3, 0x45800000, v2
	v_cndmask_b32_e32 v2, v2, v3, vcc
	v_lshl_add_u32 v3, v6, 2, 0
	v_add_u32_e32 v3, 0x22000, v3
	ds_write_b32 v3, v2
.LBB9_1198:
	s_or_b64 exec, exec, s[44:45]
	s_add_u32 s34, s85, s48
	s_addc_u32 s35, s86, s5
	v_lshlrev_b64 v[2:3], 2, v[234:235]
	v_lshl_add_u64 v[114:115], s[34:35], 0, v[2:3]
	s_and_b32 s3, s4, 0xffffff00
	s_add_i32 s3, s3, 0
	v_add_co_u32_e32 v128, vcc, s28, v114
	s_waitcnt lgkmcnt(0)
	s_barrier
	s_mov_b64 s[34:35], 0x2000
	v_lshl_add_u32 v4, v248, 2, s3
	v_lshl_add_u64 v[116:117], s[20:21], 0, v[2:3]
	v_addc_co_u32_e32 v129, vcc, 0, v115, vcc
	v_lshl_add_u64 v[130:131], v[114:115], 0, s[34:35]
	v_add_u32_e32 v140, 0x22000, v4
	s_waitcnt vmcnt(0)
	v_mov_b32_e32 v142, v150
	v_mov_b32_e32 v143, v151
	v_mov_b32_e32 v144, v152
	v_mov_b32_e32 v145, v153
	v_mov_b32_e32 v2, v154
	v_mov_b32_e32 v3, v155
	v_mov_b32_e32 v4, v156
	v_mov_b32_e32 v5, v157
	v_mov_b32_e32 v6, v158
	v_mov_b32_e32 v7, v159
	v_mov_b32_e32 v8, v160
	v_mov_b32_e32 v9, v161
	v_mov_b32_e32 v136, v162
	v_mov_b32_e32 v137, v163
	v_mov_b32_e32 v138, v164
	v_mov_b32_e32 v139, v165
	v_lshl_add_u64 v[126:127], v[234:235], 1, s[26:27]
	s_mov_b64 s[4:5], 0x2200
	s_waitcnt vmcnt(1)
	v_pk_add_f32 v[8:9], v[8:9], 1.0 op_sel_hi:[1,0]
	v_pk_add_f32 v[6:7], v[6:7], 1.0 op_sel_hi:[1,0]
	v_pk_mul_f32 v[132:133], v[4:5], v[8:9]
	v_pk_mul_f32 v[134:135], v[2:3], v[6:7]
	v_mov_b32_e32 v2, v166
	v_mov_b32_e32 v3, v167
	v_mov_b32_e32 v4, v168
	v_mov_b32_e32 v5, v169
	v_mov_b32_e32 v6, v170
	v_mov_b32_e32 v7, v171
	v_mov_b32_e32 v8, v172
	v_mov_b32_e32 v9, v173
	global_load_dwordx4 v[150:153], v[116:117], off offset:528
	global_load_dwordx4 v[154:157], v[116:117], off offset:512
	global_load_dwordx4 v[158:161], v[128:129], off offset:512
	global_load_dwordx4 v[162:165], v[130:131], off offset:528
	global_load_dwordx4 v[166:169], v[114:115], off offset:528
	global_load_dwordx4 v[170:173], v[114:115], off offset:512
	v_pk_add_f32 v[130:131], v[138:139], 1.0 op_sel_hi:[1,0]
	v_pk_add_f32 v[138:139], v[136:137], 1.0 op_sel_hi:[1,0]
	v_pk_mul_f32 v[136:137], v[144:145], v[130:131]
	ds_read_b32 v130, v140
	v_pk_mul_f32 v[138:139], v[142:143], v[138:139]
	s_waitcnt lgkmcnt(0)
	v_pk_mul_f32 v[142:143], v[230:231], v[130:131] op_sel_hi:[1,0]
	v_pk_mul_f32 v[144:145], v[232:233], v[130:131] op_sel_hi:[1,0]
	v_pk_fma_f32 v[146:147], v[132:133], v[142:143], v[8:9]
	v_pk_fma_f32 v[142:143], v[134:135], v[144:145], v[6:7]
	v_pk_mul_f32 v[144:145], v[226:227], v[130:131] op_sel_hi:[1,0]
	v_pk_mul_f32 v[130:131], v[228:229], v[130:131] op_sel_hi:[1,0]
	v_pk_fma_f32 v[148:149], v[136:137], v[144:145], v[4:5]
	v_pk_fma_f32 v[130:131], v[138:139], v[130:131], v[2:3]
	v_cvt_pk_bf16_f32 v142, v142, v143
	v_cvt_pk_bf16_f32 v143, v146, v147
	s_nop 0
	v_cvt_pk_bf16_f32 v144, v130, v131
	v_lshl_add_u64 v[130:131], v[126:127], 0, v[224:225]
	v_cvt_pk_bf16_f32 v145, v148, v149
	global_store_dwordx4 v[130:131], v[142:145], off
	ds_read_b32 v142, v140 offset:64
	s_waitcnt lgkmcnt(0)
	v_pk_mul_f32 v[110:111], v[110:111], v[142:143] op_sel_hi:[1,0]
	v_pk_mul_f32 v[106:107], v[106:107], v[142:143] op_sel_hi:[1,0]
	v_pk_mul_f32 v[112:113], v[112:113], v[142:143] op_sel_hi:[1,0]
	v_pk_fma_f32 v[110:111], v[134:135], v[110:111], v[6:7]
	v_pk_mul_f32 v[108:109], v[108:109], v[142:143] op_sel_hi:[1,0]
	v_pk_fma_f32 v[106:107], v[138:139], v[106:107], v[2:3]
	v_pk_fma_f32 v[112:113], v[132:133], v[112:113], v[8:9]
	v_pk_fma_f32 v[142:143], v[136:137], v[108:109], v[4:5]
	v_cvt_pk_bf16_f32 v108, v110, v111
	v_cvt_pk_bf16_f32 v109, v112, v113
	v_cvt_pk_bf16_f32 v110, v106, v107
	v_lshl_add_u64 v[106:107], v[126:127], 0, v[222:223]
	v_cvt_pk_bf16_f32 v111, v142, v143
	global_store_dwordx4 v[106:107], v[108:111], off
	ds_read_b32 v108, v140 offset:128
	s_waitcnt lgkmcnt(0)
; __device__ __forceinline__ unsigned cvt_pk_bf16(float lo, float hi) { unsigned r; asm volatile("v_cvt_pk_bf16_f32 %0, %1, %2" : "=v"(r) : "v"(lo), "v"(hi)); return r; }
;     __device__ __forceinline__ void fuse_tail(f32x4 (&acc)[2][2][4][2], const float (&ssq)[2][4], const Unit& u, int wr, int wc, int fr, int fq, int mi, int row0, int col0) const {
;     ...
;         bf16_t* XN = (bf16_t*)((char*)X + RN_DXN);
;         const float* sh = mods_l + nsh_off + (size_t)mi * MODW + col0;
; #pragma unroll
;         for (int bj = 0; bj < 2; ++bj) { f32x4 GG[2], SS[2];
; #pragma unroll
;             for (int n = 0; n < 2; ++n) { GG[n] = *(const f32x4*)(ng + col0 + bj * HALF + 4 * n) * (*(const f32x4*)(sh + D + bj * HALF + 4 * n) + 1.f); SS[n] = *(const f32x4*)(sh + bj * HALF + 4 * n); }
; #pragma unroll
;             for (int ai = 0; ai < 2; ++ai)
; #pragma unroll
;                 for (int m = 0; m < 4; ++m) { const float rstd = S[ai * HALF + wr * 64 + m * 16 + fr];
;                     const f32x4 h0 = acc[ai][bj][m][0] * rstd * GG[0] + SS[0], h1 = acc[ai][bj][m][1] * rstd * GG[1] + SS[1];
;                     u32x4 w; w.x = cvt_pk_bf16(h0[0], h0[1]); w.y = cvt_pk_bf16(h0[2], h0[3]); w.z = cvt_pk_bf16(h1[0], h1[1]); w.w = cvt_pk_bf16(h1[2], h1[3]);
;                     *(u32x4*)(XN + (size_t)(row0 + ai * HALF + m * 16) * D + col0 + bj * HALF) = w; } }
	v_pk_mul_f32 v[94:95], v[94:95], v[108:109] op_sel_hi:[1,0]
	v_pk_mul_f32 v[90:91], v[90:91], v[108:109] op_sel_hi:[1,0]
	v_pk_mul_f32 v[96:97], v[96:97], v[108:109] op_sel_hi:[1,0]
	v_pk_fma_f32 v[94:95], v[134:135], v[94:95], v[6:7]
	v_pk_mul_f32 v[92:93], v[92:93], v[108:109] op_sel_hi:[1,0]
	v_pk_fma_f32 v[90:91], v[138:139], v[90:91], v[2:3]
	v_pk_fma_f32 v[96:97], v[132:133], v[96:97], v[8:9]
	v_pk_fma_f32 v[108:109], v[136:137], v[92:93], v[4:5]
	v_cvt_pk_bf16_f32 v92, v94, v95
	v_cvt_pk_bf16_f32 v93, v96, v97
	v_cvt_pk_bf16_f32 v94, v90, v91
	v_lshl_add_u64 v[90:91], v[126:127], 0, v[220:221]
	v_cvt_pk_bf16_f32 v95, v108, v109
	global_store_dwordx4 v[90:91], v[92:95], off
	ds_read_b32 v92, v140 offset:192
	s_waitcnt lgkmcnt(0)
	v_pk_mul_f32 v[78:79], v[78:79], v[92:93] op_sel_hi:[1,0]
	v_pk_mul_f32 v[74:75], v[74:75], v[92:93] op_sel_hi:[1,0]
	v_pk_mul_f32 v[80:81], v[80:81], v[92:93] op_sel_hi:[1,0]
	v_pk_fma_f32 v[78:79], v[134:135], v[78:79], v[6:7]
	v_pk_mul_f32 v[76:77], v[76:77], v[92:93] op_sel_hi:[1,0]
	v_pk_fma_f32 v[74:75], v[138:139], v[74:75], v[2:3]
	v_pk_fma_f32 v[80:81], v[132:133], v[80:81], v[8:9]
	v_pk_fma_f32 v[92:93], v[136:137], v[76:77], v[4:5]
	v_cvt_pk_bf16_f32 v76, v78, v79
	v_cvt_pk_bf16_f32 v77, v80, v81
	v_cvt_pk_bf16_f32 v78, v74, v75
	v_lshl_add_u64 v[74:75], v[126:127], 0, v[216:217]
	v_cvt_pk_bf16_f32 v79, v92, v93
	global_store_dwordx4 v[74:75], v[76:79], off
	ds_read_b32 v76, v140 offset:512
	s_waitcnt lgkmcnt(0)
	v_pk_mul_f32 v[62:63], v[62:63], v[76:77] op_sel_hi:[1,0]
	v_pk_mul_f32 v[58:59], v[58:59], v[76:77] op_sel_hi:[1,0]
	v_pk_mul_f32 v[64:65], v[64:65], v[76:77] op_sel_hi:[1,0]
	v_pk_fma_f32 v[62:63], v[134:135], v[62:63], v[6:7]
	v_pk_mul_f32 v[60:61], v[60:61], v[76:77] op_sel_hi:[1,0]
	v_pk_fma_f32 v[58:59], v[138:139], v[58:59], v[2:3]
	v_pk_fma_f32 v[64:65], v[132:133], v[64:65], v[8:9]
	v_pk_fma_f32 v[76:77], v[136:137], v[60:61], v[4:5]
	v_cvt_pk_bf16_f32 v60, v62, v63
	v_cvt_pk_bf16_f32 v61, v64, v65
	v_cvt_pk_bf16_f32 v62, v58, v59
	v_lshl_add_u64 v[58:59], v[126:127], 0, v[218:219]
	v_cvt_pk_bf16_f32 v63, v76, v77
	global_store_dwordx4 v[58:59], v[60:63], off
	ds_read_b32 v60, v140 offset:576
	s_waitcnt lgkmcnt(0)
	v_pk_mul_f32 v[46:47], v[46:47], v[60:61] op_sel_hi:[1,0]
	v_pk_mul_f32 v[42:43], v[42:43], v[60:61] op_sel_hi:[1,0]
	v_pk_mul_f32 v[48:49], v[48:49], v[60:61] op_sel_hi:[1,0]
	v_pk_fma_f32 v[46:47], v[134:135], v[46:47], v[6:7]
	v_pk_mul_f32 v[44:45], v[44:45], v[60:61] op_sel_hi:[1,0]
	v_pk_fma_f32 v[42:43], v[138:139], v[42:43], v[2:3]
	v_pk_fma_f32 v[48:49], v[132:133], v[48:49], v[8:9]
	v_pk_fma_f32 v[60:61], v[136:137], v[44:45], v[4:5]
	v_cvt_pk_bf16_f32 v44, v46, v47
	v_cvt_pk_bf16_f32 v45, v48, v49
	v_cvt_pk_bf16_f32 v46, v42, v43
	v_lshl_add_u64 v[42:43], v[126:127], 0, v[214:215]
	v_cvt_pk_bf16_f32 v47, v60, v61
	global_store_dwordx4 v[42:43], v[44:47], off
	ds_read_b32 v44, v140 offset:640
	s_waitcnt lgkmcnt(0)
	v_pk_mul_f32 v[30:31], v[30:31], v[44:45] op_sel_hi:[1,0]
	v_pk_mul_f32 v[26:27], v[26:27], v[44:45] op_sel_hi:[1,0]
	v_pk_mul_f32 v[32:33], v[32:33], v[44:45] op_sel_hi:[1,0]
	v_pk_fma_f32 v[30:31], v[134:135], v[30:31], v[6:7]
	v_pk_mul_f32 v[28:29], v[28:29], v[44:45] op_sel_hi:[1,0]
	v_pk_fma_f32 v[26:27], v[138:139], v[26:27], v[2:3]
	v_pk_fma_f32 v[32:33], v[132:133], v[32:33], v[8:9]
	v_pk_fma_f32 v[44:45], v[136:137], v[28:29], v[4:5]
	v_cvt_pk_bf16_f32 v28, v30, v31
	v_cvt_pk_bf16_f32 v29, v32, v33
	v_cvt_pk_bf16_f32 v30, v26, v27
	v_lshl_add_u64 v[26:27], v[126:127], 0, v[212:213]
	v_cvt_pk_bf16_f32 v31, v44, v45
	global_store_dwordx4 v[26:27], v[28:31], off
	ds_read_b32 v28, v140 offset:704
	s_waitcnt lgkmcnt(0)
	v_pk_mul_f32 v[32:33], v[122:123], v[28:29] op_sel_hi:[1,0]
	v_pk_mul_f32 v[30:31], v[118:119], v[28:29] op_sel_hi:[1,0]
	v_pk_fma_f32 v[6:7], v[134:135], v[32:33], v[6:7]
	v_pk_fma_f32 v[8:9], v[132:133], v[30:31], v[8:9]
	v_pk_mul_f32 v[30:31], v[120:121], v[28:29] op_sel_hi:[1,0]
	v_pk_mul_f32 v[28:29], v[124:125], v[28:29] op_sel_hi:[1,0]
	v_pk_fma_f32 v[30:31], v[136:137], v[30:31], v[4:5]
	v_pk_fma_f32 v[4:5], v[138:139], v[28:29], v[2:3]
	v_lshl_add_u64 v[28:29], v[126:127], 0, v[210:211]
	v_cvt_pk_bf16_f32 v2, v6, v7
	v_cvt_pk_bf16_f32 v3, v8, v9
	v_cvt_pk_bf16_f32 v4, v4, v5
	v_cvt_pk_bf16_f32 v5, v30, v31
	global_store_dwordx4 v[28:29], v[2:5], off
	v_lshl_add_u64 v[30:31], v[114:115], 0, s[4:5]
	s_waitcnt vmcnt(8)
	v_mov_b32_e32 v46, v150
	v_mov_b32_e32 v47, v151
	v_mov_b32_e32 v48, v152
	v_mov_b32_e32 v49, v153
	v_mov_b32_e32 v2, v154
	v_mov_b32_e32 v3, v155
	v_mov_b32_e32 v4, v156
	v_mov_b32_e32 v5, v157
	v_mov_b32_e32 v6, v158
	v_mov_b32_e32 v7, v159
	v_mov_b32_e32 v8, v160
	v_mov_b32_e32 v9, v161
	v_mov_b32_e32 v60, v162
	v_mov_b32_e32 v61, v163
	v_mov_b32_e32 v62, v164
	v_mov_b32_e32 v63, v165
	v_pk_add_f32 v[8:9], v[8:9], 1.0 op_sel_hi:[1,0]
	v_pk_add_f32 v[6:7], v[6:7], 1.0 op_sel_hi:[1,0]
	v_pk_mul_f32 v[30:31], v[4:5], v[8:9]
	v_pk_mul_f32 v[32:33], v[2:3], v[6:7]
	v_mov_b32_e32 v2, v166
	v_mov_b32_e32 v3, v167
	v_mov_b32_e32 v4, v168
	v_mov_b32_e32 v5, v169
	v_mov_b32_e32 v6, v170
	v_mov_b32_e32 v7, v171
	v_mov_b32_e32 v8, v172
	v_mov_b32_e32 v9, v173
	v_pk_add_f32 v[44:45], v[62:63], 1.0 op_sel_hi:[1,0]
	v_pk_add_f32 v[60:61], v[60:61], 1.0 op_sel_hi:[1,0]
	v_pk_mul_f32 v[44:45], v[48:49], v[44:45]
	ds_read_b32 v48, v140
	v_pk_mul_f32 v[46:47], v[46:47], v[60:61]
	s_waitcnt lgkmcnt(0)
; __device__ __forceinline__ unsigned cvt_pk_bf16(float lo, float hi) { unsigned r; asm volatile("v_cvt_pk_bf16_f32 %0, %1, %2" : "=v"(r) : "v"(lo), "v"(hi)); return r; }
;     __device__ __forceinline__ void fuse_tail(f32x4 (&acc)[2][2][4][2], const float (&ssq)[2][4], const Unit& u, int wr, int wc, int fr, int fq, int mi, int row0, int col0) const {
;     ...
;         bf16_t* XN = (bf16_t*)((char*)X + RN_DXN);
;         const float* sh = mods_l + nsh_off + (size_t)mi * MODW + col0;
; #pragma unroll
;         for (int bj = 0; bj < 2; ++bj) { f32x4 GG[2], SS[2];
; #pragma unroll
;             for (int n = 0; n < 2; ++n) { GG[n] = *(const f32x4*)(ng + col0 + bj * HALF + 4 * n) * (*(const f32x4*)(sh + D + bj * HALF + 4 * n) + 1.f); SS[n] = *(const f32x4*)(sh + bj * HALF + 4 * n); }
; #pragma unroll
;             for (int ai = 0; ai < 2; ++ai)
; #pragma unroll
;                 for (int m = 0; m < 4; ++m) { const float rstd = S[ai * HALF + wr * 64 + m * 16 + fr];
;                     const f32x4 h0 = acc[ai][bj][m][0] * rstd * GG[0] + SS[0], h1 = acc[ai][bj][m][1] * rstd * GG[1] + SS[1];
;                     u32x4 w; w.x = cvt_pk_bf16(h0[0], h0[1]); w.y = cvt_pk_bf16(h0[2], h0[3]); w.z = cvt_pk_bf16(h1[0], h1[1]); w.w = cvt_pk_bf16(h1[2], h1[3]);
;                     *(u32x4*)(XN + (size_t)(row0 + ai * HALF + m * 16) * D + col0 + bj * HALF) = w; } }
	v_pk_mul_f32 v[60:61], v[206:207], v[48:49] op_sel_hi:[1,0]
	v_pk_mul_f32 v[62:63], v[208:209], v[48:49] op_sel_hi:[1,0]
	v_pk_fma_f32 v[64:65], v[30:31], v[60:61], v[8:9]
	v_pk_fma_f32 v[60:61], v[32:33], v[62:63], v[6:7]
	v_pk_mul_f32 v[62:63], v[202:203], v[48:49] op_sel_hi:[1,0]
	v_pk_mul_f32 v[48:49], v[204:205], v[48:49] op_sel_hi:[1,0]
	v_pk_fma_f32 v[76:77], v[44:45], v[62:63], v[4:5]
	v_pk_fma_f32 v[48:49], v[46:47], v[48:49], v[2:3]
	v_cvt_pk_bf16_f32 v60, v60, v61
	v_cvt_pk_bf16_f32 v61, v64, v65
	s_nop 0
	v_cvt_pk_bf16_f32 v62, v48, v49
	v_cvt_pk_bf16_f32 v63, v76, v77
	ds_read_b32 v48, v140 offset:64
	global_store_dwordx4 v[130:131], v[60:63], off offset:256
	s_waitcnt lgkmcnt(0)
	s_nop 0
	v_pk_mul_f32 v[60:61], v[104:105], v[48:49] op_sel_hi:[1,0]
	v_pk_mul_f32 v[62:63], v[102:103], v[48:49] op_sel_hi:[1,0]
	v_pk_fma_f32 v[64:65], v[30:31], v[60:61], v[8:9]
	v_pk_fma_f32 v[60:61], v[32:33], v[62:63], v[6:7]
	v_pk_mul_f32 v[62:63], v[100:101], v[48:49] op_sel_hi:[1,0]
	v_pk_mul_f32 v[48:49], v[98:99], v[48:49] op_sel_hi:[1,0]
	v_pk_fma_f32 v[76:77], v[44:45], v[62:63], v[4:5]
	v_pk_fma_f32 v[48:49], v[46:47], v[48:49], v[2:3]
	v_cvt_pk_bf16_f32 v60, v60, v61
	v_cvt_pk_bf16_f32 v61, v64, v65
	s_nop 0
	v_cvt_pk_bf16_f32 v62, v48, v49
	v_cvt_pk_bf16_f32 v63, v76, v77
	ds_read_b32 v48, v140 offset:128
	global_store_dwordx4 v[106:107], v[60:63], off offset:256
	s_waitcnt lgkmcnt(0)
	s_nop 0
	v_pk_mul_f32 v[60:61], v[88:89], v[48:49] op_sel_hi:[1,0]
	v_pk_mul_f32 v[62:63], v[86:87], v[48:49] op_sel_hi:[1,0]
	v_pk_fma_f32 v[64:65], v[30:31], v[60:61], v[8:9]
	v_pk_fma_f32 v[60:61], v[32:33], v[62:63], v[6:7]
	v_pk_mul_f32 v[62:63], v[84:85], v[48:49] op_sel_hi:[1,0]
	v_pk_mul_f32 v[48:49], v[82:83], v[48:49] op_sel_hi:[1,0]
	v_pk_fma_f32 v[76:77], v[44:45], v[62:63], v[4:5]
	v_pk_fma_f32 v[48:49], v[46:47], v[48:49], v[2:3]
	v_cvt_pk_bf16_f32 v60, v60, v61
	v_cvt_pk_bf16_f32 v61, v64, v65
	s_nop 0
	v_cvt_pk_bf16_f32 v62, v48, v49
	v_cvt_pk_bf16_f32 v63, v76, v77
	ds_read_b32 v48, v140 offset:192
	global_store_dwordx4 v[90:91], v[60:63], off offset:256
	s_waitcnt lgkmcnt(0)
	s_nop 0
	v_pk_mul_f32 v[60:61], v[72:73], v[48:49] op_sel_hi:[1,0]
	v_pk_mul_f32 v[62:63], v[70:71], v[48:49] op_sel_hi:[1,0]
	v_pk_fma_f32 v[64:65], v[30:31], v[60:61], v[8:9]
	v_pk_fma_f32 v[60:61], v[32:33], v[62:63], v[6:7]
	v_pk_mul_f32 v[62:63], v[68:69], v[48:49] op_sel_hi:[1,0]
	v_pk_mul_f32 v[48:49], v[66:67], v[48:49] op_sel_hi:[1,0]
	v_pk_fma_f32 v[66:67], v[44:45], v[62:63], v[4:5]
	v_pk_fma_f32 v[48:49], v[46:47], v[48:49], v[2:3]
	v_cvt_pk_bf16_f32 v60, v60, v61
	v_cvt_pk_bf16_f32 v61, v64, v65
	s_nop 0
	v_cvt_pk_bf16_f32 v62, v48, v49
	v_cvt_pk_bf16_f32 v63, v66, v67
	ds_read_b32 v48, v140 offset:512
	global_store_dwordx4 v[74:75], v[60:63], off offset:256
	s_waitcnt lgkmcnt(0)
	v_pk_mul_f32 v[56:57], v[56:57], v[48:49] op_sel_hi:[1,0]
	v_pk_mul_f32 v[54:55], v[54:55], v[48:49] op_sel_hi:[1,0]
	v_pk_mul_f32 v[52:53], v[52:53], v[48:49] op_sel_hi:[1,0]
	v_pk_mul_f32 v[48:49], v[50:51], v[48:49] op_sel_hi:[1,0]
	v_pk_fma_f32 v[54:55], v[32:33], v[54:55], v[6:7]
	v_pk_fma_f32 v[50:51], v[46:47], v[48:49], v[2:3]
	v_cvt_pk_bf16_f32 v48, v54, v55
	v_pk_fma_f32 v[56:57], v[30:31], v[56:57], v[8:9]
	v_pk_fma_f32 v[52:53], v[44:45], v[52:53], v[4:5]
	v_cvt_pk_bf16_f32 v49, v56, v57
	v_cvt_pk_bf16_f32 v50, v50, v51
	s_nop 0
	v_cvt_pk_bf16_f32 v51, v52, v53
	global_store_dwordx4 v[58:59], v[48:51], off offset:256
	ds_read_b32 v48, v140 offset:576
	s_waitcnt lgkmcnt(0)
	v_pk_mul_f32 v[38:39], v[38:39], v[48:49] op_sel_hi:[1,0]
	v_pk_mul_f32 v[36:37], v[36:37], v[48:49] op_sel_hi:[1,0]
	v_pk_mul_f32 v[34:35], v[34:35], v[48:49] op_sel_hi:[1,0]
	v_pk_mul_f32 v[40:41], v[40:41], v[48:49] op_sel_hi:[1,0]
	v_pk_fma_f32 v[38:39], v[32:33], v[38:39], v[6:7]
	v_pk_fma_f32 v[48:49], v[44:45], v[36:37], v[4:5]
	v_pk_fma_f32 v[36:37], v[46:47], v[34:35], v[2:3]
	v_cvt_pk_bf16_f32 v34, v38, v39
	v_pk_fma_f32 v[40:41], v[30:31], v[40:41], v[8:9]
	s_nop 0
	v_cvt_pk_bf16_f32 v35, v40, v41
	v_cvt_pk_bf16_f32 v36, v36, v37
	v_cvt_pk_bf16_f32 v37, v48, v49
	global_store_dwordx4 v[42:43], v[34:37], off offset:256
	ds_read_b32 v34, v140 offset:640
	s_waitcnt lgkmcnt(0)
	v_pk_mul_f32 v[22:23], v[22:23], v[34:35] op_sel_hi:[1,0]
	v_pk_mul_f32 v[20:21], v[20:21], v[34:35] op_sel_hi:[1,0]
	v_pk_mul_f32 v[18:19], v[18:19], v[34:35] op_sel_hi:[1,0]
	v_pk_mul_f32 v[24:25], v[24:25], v[34:35] op_sel_hi:[1,0]
	v_pk_fma_f32 v[22:23], v[32:33], v[22:23], v[6:7]
	v_pk_fma_f32 v[34:35], v[44:45], v[20:21], v[4:5]
	v_pk_fma_f32 v[20:21], v[46:47], v[18:19], v[2:3]
	v_cvt_pk_bf16_f32 v18, v22, v23
	v_pk_fma_f32 v[24:25], v[30:31], v[24:25], v[8:9]
	s_nop 0
	v_cvt_pk_bf16_f32 v19, v24, v25
	v_cvt_pk_bf16_f32 v20, v20, v21
	v_cvt_pk_bf16_f32 v21, v34, v35
	global_store_dwordx4 v[26:27], v[18:21], off offset:256
	ds_read_b32 v18, v140 offset:704
	s_waitcnt lgkmcnt(0)
	v_pk_mul_f32 v[12:13], v[12:13], v[18:19] op_sel_hi:[1,0]
	s_nop 0
	v_pk_fma_f32 v[8:9], v[30:31], v[12:13], v[8:9]
	v_pk_mul_f32 v[10:11], v[10:11], v[18:19] op_sel_hi:[1,0]
	v_pk_mul_f32 v[12:13], v[14:15], v[18:19] op_sel_hi:[1,0]
	v_pk_mul_f32 v[16:17], v[16:17], v[18:19] op_sel_hi:[1,0]
	v_pk_fma_f32 v[10:11], v[44:45], v[10:11], v[4:5]
	v_pk_fma_f32 v[4:5], v[46:47], v[12:13], v[2:3]
	v_pk_fma_f32 v[6:7], v[32:33], v[16:17], v[6:7]
	s_nop 0
	v_cvt_pk_bf16_f32 v2, v6, v7
	v_cvt_pk_bf16_f32 v3, v8, v9
	v_cvt_pk_bf16_f32 v4, v4, v5
	v_cvt_pk_bf16_f32 v5, v10, v11
	global_store_dwordx4 v[28:29], v[2:5], off offset:256
	s_and_b64 vcc, exec, s[38:39]
	s_mov_b64 s[34:35], -1
	s_cbranch_vccnz .LBB9_1129

;     __device__ __forceinline__ void fuse_tail(f32x4 (&acc)[2][2][4][2], const float (&ssq)[2][4], const Unit& u, int wr, int wc, int fr, int fq, int mi, int row0, int col0) const {
;     ...
;         if (wid == 0) { unsigned sp = 0u;
;             while ((unsigned)__builtin_amdgcn_readfirstlane((int)__hip_atomic_load(pc, __ATOMIC_RELAXED, __HIP_MEMORY_SCOPE_AGENT)) < want) { __builtin_amdgcn_s_sleep(1); if (++sp > (1u << 18)) break; }
;             __builtin_amdgcn_fence(__ATOMIC_ACQUIRE, "agent"); }
;         asm volatile("s_waitcnt lgkmcnt(0)" ::: "memory"); __builtin_amdgcn_s_barrier(); asm volatile("" ::: "memory");
;         if (lane < 32) { float t = 0.f;
; #pragma unroll
;             for (int k = 0; k < 8; ++k) t += __builtin_bit_cast(float, __hip_atomic_load(slots + k, __ATOMIC_RELAXED, __HIP_MEMORY_SCOPE_AGENT));
;             S[row] = rsqrtf(t * (1.f / D) + 1e-6f); }
;         asm volatile("s_waitcnt lgkmcnt(0)" ::: "memory"); __builtin_amdgcn_s_barrier(); asm volatile("" ::: "memory");
;         if (FUSE == 2) {
;             float* ob = slab + (size_t)row0 * D + col0;
; #pragma unroll
;             for (int bj = 0; bj < 2; ++bj) { const f32x4 G0 = *(const f32x4*)(ng + col0 + bj * HALF), G1 = *(const f32x4*)(ng + col0 + bj * HALF + 4);
; #pragma unroll
;                 for (int ai = 0; ai < 2; ++ai)
; #pragma unroll
;                     for (int m = 0; m < 4; ++m) { const float rstd = S[ai * HALF + wr * 64 + m * 16 + fr];
;                         *(f32x4*)(ob + (size_t)(ai * HALF + m * 16) * D + bj * HALF) = acc[ai][bj][m][0] * rstd * G0; *(f32x4*)(ob + (size_t)(ai * HALF + m * 16) * D + bj * HALF + 4) = acc[ai][bj][m][1] * rstd * G1; } }
;             return;
;         }
;         bf16_t* XN = (bf16_t*)((char*)X + RN_DXN);
;         const float* sh = mods_l + nsh_off + (size_t)mi * MODW + col0;
; #pragma unroll
;         for (int bj = 0; bj < 2; ++bj) { f32x4 GG[2], SS[2];
; #pragma unroll
;             for (int n = 0; n < 2; ++n) { GG[n] = *(const f32x4*)(ng + col0 + bj * HALF + 4 * n) * (*(const f32x4*)(sh + D + bj * HALF + 4 * n) + 1.f); SS[n] = *(const f32x4*)(sh + bj * HALF + 4 * n); }
; #pragma unroll
;             for (int ai = 0; ai < 2; ++ai)
; #pragma unroll
;                 for (int m = 0; m < 4; ++m) { const float rstd = S[ai * HALF + wr * 64 + m * 16 + fr];
.LBB9_1593:
	s_add_u32 s98, s85, s27
	s_addc_u32 s99, s86, s5
	v_lshlrev_b64 v[174:175], 2, v[234:235]
	v_lshl_add_u64 v[176:177], s[98:99], 0, v[174:175]
	v_lshl_add_u64 v[178:179], s[18:19], 0, v[174:175]
	s_mov_b32 s98, s28
	s_mov_b32 s99, 0
	v_lshl_add_u64 v[180:181], v[176:177], 0, s[98:99]
	s_mov_b64 s[98:99], 0x2000
	v_lshl_add_u64 v[182:183], v[176:177], 0, s[98:99]
	global_load_dwordx4 v[150:153], v[178:179], off offset:16
	global_load_dwordx4 v[154:157], v[178:179], off
	global_load_dwordx4 v[158:161], v[180:181], off
	global_load_dwordx4 v[162:165], v[182:183], off offset:16
	global_load_dwordx4 v[166:169], v[176:177], off offset:16
	global_load_dwordx4 v[170:173], v[176:177], off
	s_waitcnt lgkmcnt(0)
	s_barrier
	s_and_saveexec_b64 s[44:45], s[40:41]
	s_cbranch_execz .LBB9_1595
	global_load_dword v4, v[2:3], off sc1
	global_load_dword v5, v[2:3], off offset:4 sc1
	global_load_dword v7, v[2:3], off offset:8 sc1
	global_load_dword v8, v[2:3], off offset:12 sc1
	global_load_dword v9, v[2:3], off offset:16 sc1
	global_load_dword v130, v[2:3], off offset:20 sc1
	global_load_dword v131, v[2:3], off offset:24 sc1
	global_load_dword v132, v[2:3], off offset:28 sc1
	s_waitcnt vmcnt(7)
	v_add_f32_e32 v4, 0, v4
	s_waitcnt vmcnt(6)
	v_add_f32_e32 v4, v4, v5
	s_waitcnt vmcnt(5)
	v_add_f32_e32 v4, v4, v7
	s_waitcnt vmcnt(4)
	v_add_f32_e32 v4, v4, v8
	s_waitcnt vmcnt(3)
	v_add_f32_e32 v4, v4, v9
	s_waitcnt vmcnt(2)
	v_add_f32_e32 v4, v4, v130
	s_waitcnt vmcnt(1)
	v_add_f32_e32 v4, v4, v131
	s_waitcnt vmcnt(0)
	v_add_f32_e32 v2, v4, v132
	v_fmamk_f32 v2, v2, 0x3a000000, v238
	v_cmp_gt_f32_e32 vcc, s94, v2
	v_mul_f32_e32 v3, 0x4b800000, v2
	s_nop 0
	v_cndmask_b32_e32 v2, v2, v3, vcc
	v_rsq_f32_e32 v2, v2
	s_nop 0
	v_mul_f32_e32 v3, 0x45800000, v2
	v_cndmask_b32_e32 v2, v2, v3, vcc
	v_lshl_add_u32 v3, v6, 2, 0
	v_add_u32_e32 v3, 0x22000, v3
	ds_write_b32 v3, v2
.LBB9_1595:
	s_or_b64 exec, exec, s[44:45]
	s_add_u32 s40, s85, s27
	s_addc_u32 s41, s86, s5
	v_lshlrev_b64 v[2:3], 2, v[234:235]
	v_lshl_add_u64 v[114:115], s[40:41], 0, v[2:3]
	s_and_b32 s3, s4, 0xffffff00
	s_add_i32 s3, s3, 0
	v_add_co_u32_e32 v128, vcc, s28, v114
	s_waitcnt lgkmcnt(0)
	s_barrier
	s_mov_b64 s[40:41], 0x2000
	v_lshl_add_u32 v4, v248, 2, s3
	v_lshl_add_u64 v[116:117], s[18:19], 0, v[2:3]
	v_addc_co_u32_e32 v129, vcc, 0, v115, vcc
	v_lshl_add_u64 v[130:131], v[114:115], 0, s[40:41]
	v_add_u32_e32 v140, 0x22000, v4
	s_waitcnt vmcnt(0)
	v_mov_b32_e32 v142, v150
	v_mov_b32_e32 v143, v151
	v_mov_b32_e32 v144, v152
	v_mov_b32_e32 v145, v153
	v_mov_b32_e32 v2, v154
	v_mov_b32_e32 v3, v155
	v_mov_b32_e32 v4, v156
	v_mov_b32_e32 v5, v157
	v_mov_b32_e32 v6, v158
	v_mov_b32_e32 v7, v159
	v_mov_b32_e32 v8, v160
	v_mov_b32_e32 v9, v161
	v_mov_b32_e32 v136, v162
	v_mov_b32_e32 v137, v163
	v_mov_b32_e32 v138, v164
	v_mov_b32_e32 v139, v165
	v_lshl_add_u64 v[126:127], v[234:235], 1, s[24:25]
	s_mov_b64 s[4:5], 0x2200
	s_waitcnt vmcnt(1)
	v_pk_add_f32 v[8:9], v[8:9], 1.0 op_sel_hi:[1,0]
	v_pk_add_f32 v[6:7], v[6:7], 1.0 op_sel_hi:[1,0]
	v_pk_mul_f32 v[132:133], v[4:5], v[8:9]
	v_pk_mul_f32 v[134:135], v[2:3], v[6:7]
	v_mov_b32_e32 v2, v166
	v_mov_b32_e32 v3, v167
	v_mov_b32_e32 v4, v168
	v_mov_b32_e32 v5, v169
	v_mov_b32_e32 v6, v170
	v_mov_b32_e32 v7, v171
	v_mov_b32_e32 v8, v172
	v_mov_b32_e32 v9, v173
	global_load_dwordx4 v[150:153], v[116:117], off offset:528
	global_load_dwordx4 v[154:157], v[116:117], off offset:512
	global_load_dwordx4 v[158:161], v[128:129], off offset:512
	global_load_dwordx4 v[162:165], v[130:131], off offset:528
	global_load_dwordx4 v[166:169], v[114:115], off offset:528
	global_load_dwordx4 v[170:173], v[114:115], off offset:512
	v_pk_add_f32 v[130:131], v[138:139], 1.0 op_sel_hi:[1,0]
	v_pk_add_f32 v[138:139], v[136:137], 1.0 op_sel_hi:[1,0]
	v_pk_mul_f32 v[136:137], v[144:145], v[130:131]
	ds_read_b32 v130, v140
	v_pk_mul_f32 v[138:139], v[142:143], v[138:139]
	s_waitcnt lgkmcnt(0)
	v_pk_mul_f32 v[142:143], v[230:231], v[130:131] op_sel_hi:[1,0]
	v_pk_mul_f32 v[144:145], v[232:233], v[130:131] op_sel_hi:[1,0]
	v_pk_fma_f32 v[146:147], v[132:133], v[142:143], v[8:9]
	v_pk_fma_f32 v[142:143], v[134:135], v[144:145], v[6:7]
	v_pk_mul_f32 v[144:145], v[226:227], v[130:131] op_sel_hi:[1,0]
	v_pk_mul_f32 v[130:131], v[228:229], v[130:131] op_sel_hi:[1,0]
	v_pk_fma_f32 v[148:149], v[136:137], v[144:145], v[4:5]
	v_pk_fma_f32 v[130:131], v[138:139], v[130:131], v[2:3]
	v_cvt_pk_bf16_f32 v142, v142, v143
	v_cvt_pk_bf16_f32 v143, v146, v147
	s_nop 0
	v_cvt_pk_bf16_f32 v144, v130, v131
	v_lshl_add_u64 v[130:131], v[126:127], 0, v[224:225]
	v_cvt_pk_bf16_f32 v145, v148, v149
	global_store_dwordx4 v[130:131], v[142:145], off
	ds_read_b32 v142, v140 offset:64
	s_waitcnt lgkmcnt(0)
	v_pk_mul_f32 v[110:111], v[110:111], v[142:143] op_sel_hi:[1,0]
	v_pk_mul_f32 v[106:107], v[106:107], v[142:143] op_sel_hi:[1,0]
	v_pk_mul_f32 v[112:113], v[112:113], v[142:143] op_sel_hi:[1,0]
	v_pk_fma_f32 v[110:111], v[134:135], v[110:111], v[6:7]
	v_pk_mul_f32 v[108:109], v[108:109], v[142:143] op_sel_hi:[1,0]
	v_pk_fma_f32 v[106:107], v[138:139], v[106:107], v[2:3]
	v_pk_fma_f32 v[112:113], v[132:133], v[112:113], v[8:9]
	v_pk_fma_f32 v[142:143], v[136:137], v[108:109], v[4:5]
	v_cvt_pk_bf16_f32 v108, v110, v111
	v_cvt_pk_bf16_f32 v109, v112, v113
	v_cvt_pk_bf16_f32 v110, v106, v107
	v_lshl_add_u64 v[106:107], v[126:127], 0, v[222:223]
	v_cvt_pk_bf16_f32 v111, v142, v143
	global_store_dwordx4 v[106:107], v[108:111], off
	ds_read_b32 v108, v140 offset:128
	s_waitcnt lgkmcnt(0)
; __device__ __forceinline__ unsigned cvt_pk_bf16(float lo, float hi) { unsigned r; asm volatile("v_cvt_pk_bf16_f32 %0, %1, %2" : "=v"(r) : "v"(lo), "v"(hi)); return r; }
;     __device__ __forceinline__ void fuse_tail(f32x4 (&acc)[2][2][4][2], const float (&ssq)[2][4], const Unit& u, int wr, int wc, int fr, int fq, int mi, int row0, int col0) const {
;     ...
;         bf16_t* XN = (bf16_t*)((char*)X + RN_DXN);
;         const float* sh = mods_l + nsh_off + (size_t)mi * MODW + col0;
; #pragma unroll
;         for (int bj = 0; bj < 2; ++bj) { f32x4 GG[2], SS[2];
; #pragma unroll
;             for (int n = 0; n < 2; ++n) { GG[n] = *(const f32x4*)(ng + col0 + bj * HALF + 4 * n) * (*(const f32x4*)(sh + D + bj * HALF + 4 * n) + 1.f); SS[n] = *(const f32x4*)(sh + bj * HALF + 4 * n); }
; #pragma unroll
;             for (int ai = 0; ai < 2; ++ai)
; #pragma unroll
;                 for (int m = 0; m < 4; ++m) { const float rstd = S[ai * HALF + wr * 64 + m * 16 + fr];
;                     const f32x4 h0 = acc[ai][bj][m][0] * rstd * GG[0] + SS[0], h1 = acc[ai][bj][m][1] * rstd * GG[1] + SS[1];
;                     u32x4 w; w.x = cvt_pk_bf16(h0[0], h0[1]); w.y = cvt_pk_bf16(h0[2], h0[3]); w.z = cvt_pk_bf16(h1[0], h1[1]); w.w = cvt_pk_bf16(h1[2], h1[3]);
;                     *(u32x4*)(XN + (size_t)(row0 + ai * HALF + m * 16) * D + col0 + bj * HALF) = w; } }
	v_pk_mul_f32 v[94:95], v[94:95], v[108:109] op_sel_hi:[1,0]
	v_pk_mul_f32 v[90:91], v[90:91], v[108:109] op_sel_hi:[1,0]
	v_pk_mul_f32 v[96:97], v[96:97], v[108:109] op_sel_hi:[1,0]
	v_pk_fma_f32 v[94:95], v[134:135], v[94:95], v[6:7]
	v_pk_mul_f32 v[92:93], v[92:93], v[108:109] op_sel_hi:[1,0]
	v_pk_fma_f32 v[90:91], v[138:139], v[90:91], v[2:3]
	v_pk_fma_f32 v[96:97], v[132:133], v[96:97], v[8:9]
	v_pk_fma_f32 v[108:109], v[136:137], v[92:93], v[4:5]
	v_cvt_pk_bf16_f32 v92, v94, v95
	v_cvt_pk_bf16_f32 v93, v96, v97
	v_cvt_pk_bf16_f32 v94, v90, v91
	v_lshl_add_u64 v[90:91], v[126:127], 0, v[220:221]
	v_cvt_pk_bf16_f32 v95, v108, v109
	global_store_dwordx4 v[90:91], v[92:95], off
	ds_read_b32 v92, v140 offset:192
	s_waitcnt lgkmcnt(0)
	v_pk_mul_f32 v[78:79], v[78:79], v[92:93] op_sel_hi:[1,0]
	v_pk_mul_f32 v[74:75], v[74:75], v[92:93] op_sel_hi:[1,0]
	v_pk_mul_f32 v[80:81], v[80:81], v[92:93] op_sel_hi:[1,0]
	v_pk_fma_f32 v[78:79], v[134:135], v[78:79], v[6:7]
	v_pk_mul_f32 v[76:77], v[76:77], v[92:93] op_sel_hi:[1,0]
	v_pk_fma_f32 v[74:75], v[138:139], v[74:75], v[2:3]
	v_pk_fma_f32 v[80:81], v[132:133], v[80:81], v[8:9]
	v_pk_fma_f32 v[92:93], v[136:137], v[76:77], v[4:5]
	v_cvt_pk_bf16_f32 v76, v78, v79
	v_cvt_pk_bf16_f32 v77, v80, v81
	v_cvt_pk_bf16_f32 v78, v74, v75
	v_lshl_add_u64 v[74:75], v[126:127], 0, v[216:217]
	v_cvt_pk_bf16_f32 v79, v92, v93
	global_store_dwordx4 v[74:75], v[76:79], off
	ds_read_b32 v76, v140 offset:512
	s_waitcnt lgkmcnt(0)
	v_pk_mul_f32 v[62:63], v[62:63], v[76:77] op_sel_hi:[1,0]
	v_pk_mul_f32 v[58:59], v[58:59], v[76:77] op_sel_hi:[1,0]
	v_pk_mul_f32 v[64:65], v[64:65], v[76:77] op_sel_hi:[1,0]
	v_pk_fma_f32 v[62:63], v[134:135], v[62:63], v[6:7]
	v_pk_mul_f32 v[60:61], v[60:61], v[76:77] op_sel_hi:[1,0]
	v_pk_fma_f32 v[58:59], v[138:139], v[58:59], v[2:3]
	v_pk_fma_f32 v[64:65], v[132:133], v[64:65], v[8:9]
	v_pk_fma_f32 v[76:77], v[136:137], v[60:61], v[4:5]
	v_cvt_pk_bf16_f32 v60, v62, v63
	v_cvt_pk_bf16_f32 v61, v64, v65
	v_cvt_pk_bf16_f32 v62, v58, v59
	v_lshl_add_u64 v[58:59], v[126:127], 0, v[218:219]
	v_cvt_pk_bf16_f32 v63, v76, v77
	global_store_dwordx4 v[58:59], v[60:63], off
	ds_read_b32 v60, v140 offset:576
	s_waitcnt lgkmcnt(0)
	v_pk_mul_f32 v[46:47], v[46:47], v[60:61] op_sel_hi:[1,0]
	v_pk_mul_f32 v[42:43], v[42:43], v[60:61] op_sel_hi:[1,0]
	v_pk_mul_f32 v[48:49], v[48:49], v[60:61] op_sel_hi:[1,0]
	v_pk_fma_f32 v[46:47], v[134:135], v[46:47], v[6:7]
	v_pk_mul_f32 v[44:45], v[44:45], v[60:61] op_sel_hi:[1,0]
	v_pk_fma_f32 v[42:43], v[138:139], v[42:43], v[2:3]
	v_pk_fma_f32 v[48:49], v[132:133], v[48:49], v[8:9]
	v_pk_fma_f32 v[60:61], v[136:137], v[44:45], v[4:5]
	v_cvt_pk_bf16_f32 v44, v46, v47
	v_cvt_pk_bf16_f32 v45, v48, v49
	v_cvt_pk_bf16_f32 v46, v42, v43
	v_lshl_add_u64 v[42:43], v[126:127], 0, v[214:215]
	v_cvt_pk_bf16_f32 v47, v60, v61
	global_store_dwordx4 v[42:43], v[44:47], off
	ds_read_b32 v44, v140 offset:640
	s_waitcnt lgkmcnt(0)
	v_pk_mul_f32 v[30:31], v[30:31], v[44:45] op_sel_hi:[1,0]
	v_pk_mul_f32 v[26:27], v[26:27], v[44:45] op_sel_hi:[1,0]
	v_pk_mul_f32 v[32:33], v[32:33], v[44:45] op_sel_hi:[1,0]
	v_pk_fma_f32 v[30:31], v[134:135], v[30:31], v[6:7]
	v_pk_mul_f32 v[28:29], v[28:29], v[44:45] op_sel_hi:[1,0]
	v_pk_fma_f32 v[26:27], v[138:139], v[26:27], v[2:3]
	v_pk_fma_f32 v[32:33], v[132:133], v[32:33], v[8:9]
	v_pk_fma_f32 v[44:45], v[136:137], v[28:29], v[4:5]
	v_cvt_pk_bf16_f32 v28, v30, v31
	v_cvt_pk_bf16_f32 v29, v32, v33
	v_cvt_pk_bf16_f32 v30, v26, v27
	v_lshl_add_u64 v[26:27], v[126:127], 0, v[212:213]
	v_cvt_pk_bf16_f32 v31, v44, v45
	global_store_dwordx4 v[26:27], v[28:31], off
	ds_read_b32 v28, v140 offset:704
	s_waitcnt lgkmcnt(0)
	v_pk_mul_f32 v[32:33], v[122:123], v[28:29] op_sel_hi:[1,0]
	v_pk_mul_f32 v[30:31], v[118:119], v[28:29] op_sel_hi:[1,0]
	v_pk_fma_f32 v[6:7], v[134:135], v[32:33], v[6:7]
	v_pk_fma_f32 v[8:9], v[132:133], v[30:31], v[8:9]
	v_pk_mul_f32 v[30:31], v[120:121], v[28:29] op_sel_hi:[1,0]
	v_pk_mul_f32 v[28:29], v[124:125], v[28:29] op_sel_hi:[1,0]
	v_pk_fma_f32 v[30:31], v[136:137], v[30:31], v[4:5]
	v_pk_fma_f32 v[4:5], v[138:139], v[28:29], v[2:3]
	v_lshl_add_u64 v[28:29], v[126:127], 0, v[210:211]
	v_cvt_pk_bf16_f32 v2, v6, v7
	v_cvt_pk_bf16_f32 v3, v8, v9
	v_cvt_pk_bf16_f32 v4, v4, v5
	v_cvt_pk_bf16_f32 v5, v30, v31
	global_store_dwordx4 v[28:29], v[2:5], off
	v_lshl_add_u64 v[30:31], v[114:115], 0, s[4:5]
	s_waitcnt vmcnt(8)
	v_mov_b32_e32 v46, v150
	v_mov_b32_e32 v47, v151
	v_mov_b32_e32 v48, v152
	v_mov_b32_e32 v49, v153
	v_mov_b32_e32 v2, v154
	v_mov_b32_e32 v3, v155
	v_mov_b32_e32 v4, v156
	v_mov_b32_e32 v5, v157
	v_mov_b32_e32 v6, v158
	v_mov_b32_e32 v7, v159
	v_mov_b32_e32 v8, v160
	v_mov_b32_e32 v9, v161
	v_mov_b32_e32 v60, v162
	v_mov_b32_e32 v61, v163
	v_mov_b32_e32 v62, v164
	v_mov_b32_e32 v63, v165
	v_pk_add_f32 v[8:9], v[8:9], 1.0 op_sel_hi:[1,0]
	v_pk_add_f32 v[6:7], v[6:7], 1.0 op_sel_hi:[1,0]
	v_pk_mul_f32 v[30:31], v[4:5], v[8:9]
	v_pk_mul_f32 v[32:33], v[2:3], v[6:7]
	v_mov_b32_e32 v2, v166
	v_mov_b32_e32 v3, v167
	v_mov_b32_e32 v4, v168
	v_mov_b32_e32 v5, v169
	v_mov_b32_e32 v6, v170
	v_mov_b32_e32 v7, v171
	v_mov_b32_e32 v8, v172
	v_mov_b32_e32 v9, v173
	v_pk_add_f32 v[44:45], v[62:63], 1.0 op_sel_hi:[1,0]
	v_pk_add_f32 v[60:61], v[60:61], 1.0 op_sel_hi:[1,0]
	v_pk_mul_f32 v[44:45], v[48:49], v[44:45]
	ds_read_b32 v48, v140
	v_pk_mul_f32 v[46:47], v[46:47], v[60:61]
	s_waitcnt lgkmcnt(0)
; __device__ __forceinline__ unsigned cvt_pk_bf16(float lo, float hi) { unsigned r; asm volatile("v_cvt_pk_bf16_f32 %0, %1, %2" : "=v"(r) : "v"(lo), "v"(hi)); return r; }
;     __device__ __forceinline__ void fuse_tail(f32x4 (&acc)[2][2][4][2], const float (&ssq)[2][4], const Unit& u, int wr, int wc, int fr, int fq, int mi, int row0, int col0) const {
;     ...
;         bf16_t* XN = (bf16_t*)((char*)X + RN_DXN);
;         const float* sh = mods_l + nsh_off + (size_t)mi * MODW + col0;
; #pragma unroll
;         for (int bj = 0; bj < 2; ++bj) { f32x4 GG[2], SS[2];
; #pragma unroll
;             for (int n = 0; n < 2; ++n) { GG[n] = *(const f32x4*)(ng + col0 + bj * HALF + 4 * n) * (*(const f32x4*)(sh + D + bj * HALF + 4 * n) + 1.f); SS[n] = *(const f32x4*)(sh + bj * HALF + 4 * n); }
; #pragma unroll
;             for (int ai = 0; ai < 2; ++ai)
; #pragma unroll
;                 for (int m = 0; m < 4; ++m) { const float rstd = S[ai * HALF + wr * 64 + m * 16 + fr];
;                     const f32x4 h0 = acc[ai][bj][m][0] * rstd * GG[0] + SS[0], h1 = acc[ai][bj][m][1] * rstd * GG[1] + SS[1];
;                     u32x4 w; w.x = cvt_pk_bf16(h0[0], h0[1]); w.y = cvt_pk_bf16(h0[2], h0[3]); w.z = cvt_pk_bf16(h1[0], h1[1]); w.w = cvt_pk_bf16(h1[2], h1[3]);
;                     *(u32x4*)(XN + (size_t)(row0 + ai * HALF + m * 16) * D + col0 + bj * HALF) = w; } }
	v_pk_mul_f32 v[60:61], v[206:207], v[48:49] op_sel_hi:[1,0]
	v_pk_mul_f32 v[62:63], v[208:209], v[48:49] op_sel_hi:[1,0]
	v_pk_fma_f32 v[64:65], v[30:31], v[60:61], v[8:9]
	v_pk_fma_f32 v[60:61], v[32:33], v[62:63], v[6:7]
	v_pk_mul_f32 v[62:63], v[202:203], v[48:49] op_sel_hi:[1,0]
	v_pk_mul_f32 v[48:49], v[204:205], v[48:49] op_sel_hi:[1,0]
	v_pk_fma_f32 v[76:77], v[44:45], v[62:63], v[4:5]
	v_pk_fma_f32 v[48:49], v[46:47], v[48:49], v[2:3]
	v_cvt_pk_bf16_f32 v60, v60, v61
	v_cvt_pk_bf16_f32 v61, v64, v65
	s_nop 0
	v_cvt_pk_bf16_f32 v62, v48, v49
	v_cvt_pk_bf16_f32 v63, v76, v77
	ds_read_b32 v48, v140 offset:64
	global_store_dwordx4 v[130:131], v[60:63], off offset:256
	s_waitcnt lgkmcnt(0)
	s_nop 0
	v_pk_mul_f32 v[60:61], v[104:105], v[48:49] op_sel_hi:[1,0]
	v_pk_mul_f32 v[62:63], v[102:103], v[48:49] op_sel_hi:[1,0]
	v_pk_fma_f32 v[64:65], v[30:31], v[60:61], v[8:9]
	v_pk_fma_f32 v[60:61], v[32:33], v[62:63], v[6:7]
	v_pk_mul_f32 v[62:63], v[100:101], v[48:49] op_sel_hi:[1,0]
	v_pk_mul_f32 v[48:49], v[98:99], v[48:49] op_sel_hi:[1,0]
	v_pk_fma_f32 v[76:77], v[44:45], v[62:63], v[4:5]
	v_pk_fma_f32 v[48:49], v[46:47], v[48:49], v[2:3]
	v_cvt_pk_bf16_f32 v60, v60, v61
	v_cvt_pk_bf16_f32 v61, v64, v65
	s_nop 0
	v_cvt_pk_bf16_f32 v62, v48, v49
	v_cvt_pk_bf16_f32 v63, v76, v77
	ds_read_b32 v48, v140 offset:128
	global_store_dwordx4 v[106:107], v[60:63], off offset:256
	s_waitcnt lgkmcnt(0)
	s_nop 0
	v_pk_mul_f32 v[60:61], v[88:89], v[48:49] op_sel_hi:[1,0]
	v_pk_mul_f32 v[62:63], v[86:87], v[48:49] op_sel_hi:[1,0]
	v_pk_fma_f32 v[64:65], v[30:31], v[60:61], v[8:9]
	v_pk_fma_f32 v[60:61], v[32:33], v[62:63], v[6:7]
	v_pk_mul_f32 v[62:63], v[84:85], v[48:49] op_sel_hi:[1,0]
	v_pk_mul_f32 v[48:49], v[82:83], v[48:49] op_sel_hi:[1,0]
	v_pk_fma_f32 v[76:77], v[44:45], v[62:63], v[4:5]
	v_pk_fma_f32 v[48:49], v[46:47], v[48:49], v[2:3]
	v_cvt_pk_bf16_f32 v60, v60, v61
	v_cvt_pk_bf16_f32 v61, v64, v65
	s_nop 0
	v_cvt_pk_bf16_f32 v62, v48, v49
	v_cvt_pk_bf16_f32 v63, v76, v77
	ds_read_b32 v48, v140 offset:192
	global_store_dwordx4 v[90:91], v[60:63], off offset:256
	s_waitcnt lgkmcnt(0)
	s_nop 0
	v_pk_mul_f32 v[60:61], v[72:73], v[48:49] op_sel_hi:[1,0]
	v_pk_mul_f32 v[62:63], v[70:71], v[48:49] op_sel_hi:[1,0]
	v_pk_fma_f32 v[64:65], v[30:31], v[60:61], v[8:9]
	v_pk_fma_f32 v[60:61], v[32:33], v[62:63], v[6:7]
	v_pk_mul_f32 v[62:63], v[68:69], v[48:49] op_sel_hi:[1,0]
	v_pk_mul_f32 v[48:49], v[66:67], v[48:49] op_sel_hi:[1,0]
	v_pk_fma_f32 v[66:67], v[44:45], v[62:63], v[4:5]
	v_pk_fma_f32 v[48:49], v[46:47], v[48:49], v[2:3]
	v_cvt_pk_bf16_f32 v60, v60, v61
	v_cvt_pk_bf16_f32 v61, v64, v65
	s_nop 0
	v_cvt_pk_bf16_f32 v62, v48, v49
	v_cvt_pk_bf16_f32 v63, v66, v67
	ds_read_b32 v48, v140 offset:512
	global_store_dwordx4 v[74:75], v[60:63], off offset:256
	s_waitcnt lgkmcnt(0)
	v_pk_mul_f32 v[56:57], v[56:57], v[48:49] op_sel_hi:[1,0]
	v_pk_mul_f32 v[54:55], v[54:55], v[48:49] op_sel_hi:[1,0]
	v_pk_mul_f32 v[52:53], v[52:53], v[48:49] op_sel_hi:[1,0]
	v_pk_mul_f32 v[48:49], v[50:51], v[48:49] op_sel_hi:[1,0]
	v_pk_fma_f32 v[54:55], v[32:33], v[54:55], v[6:7]
	v_pk_fma_f32 v[50:51], v[46:47], v[48:49], v[2:3]
	v_cvt_pk_bf16_f32 v48, v54, v55
	v_pk_fma_f32 v[56:57], v[30:31], v[56:57], v[8:9]
	v_pk_fma_f32 v[52:53], v[44:45], v[52:53], v[4:5]
	v_cvt_pk_bf16_f32 v49, v56, v57
	v_cvt_pk_bf16_f32 v50, v50, v51
	s_nop 0
	v_cvt_pk_bf16_f32 v51, v52, v53
	global_store_dwordx4 v[58:59], v[48:51], off offset:256
	ds_read_b32 v48, v140 offset:576
	s_waitcnt lgkmcnt(0)
	v_pk_mul_f32 v[38:39], v[38:39], v[48:49] op_sel_hi:[1,0]
	v_pk_mul_f32 v[36:37], v[36:37], v[48:49] op_sel_hi:[1,0]
	v_pk_mul_f32 v[34:35], v[34:35], v[48:49] op_sel_hi:[1,0]
	v_pk_mul_f32 v[40:41], v[40:41], v[48:49] op_sel_hi:[1,0]
	v_pk_fma_f32 v[38:39], v[32:33], v[38:39], v[6:7]
	v_pk_fma_f32 v[48:49], v[44:45], v[36:37], v[4:5]
	v_pk_fma_f32 v[36:37], v[46:47], v[34:35], v[2:3]
	v_cvt_pk_bf16_f32 v34, v38, v39
	v_pk_fma_f32 v[40:41], v[30:31], v[40:41], v[8:9]
	s_nop 0
	v_cvt_pk_bf16_f32 v35, v40, v41
	v_cvt_pk_bf16_f32 v36, v36, v37
	v_cvt_pk_bf16_f32 v37, v48, v49
	global_store_dwordx4 v[42:43], v[34:37], off offset:256
	ds_read_b32 v34, v140 offset:640
	s_waitcnt lgkmcnt(0)
	v_pk_mul_f32 v[22:23], v[22:23], v[34:35] op_sel_hi:[1,0]
	v_pk_mul_f32 v[20:21], v[20:21], v[34:35] op_sel_hi:[1,0]
	v_pk_mul_f32 v[18:19], v[18:19], v[34:35] op_sel_hi:[1,0]
	v_pk_mul_f32 v[24:25], v[24:25], v[34:35] op_sel_hi:[1,0]
	v_pk_fma_f32 v[22:23], v[32:33], v[22:23], v[6:7]
	v_pk_fma_f32 v[34:35], v[44:45], v[20:21], v[4:5]
	v_pk_fma_f32 v[20:21], v[46:47], v[18:19], v[2:3]
	v_cvt_pk_bf16_f32 v18, v22, v23
	v_pk_fma_f32 v[24:25], v[30:31], v[24:25], v[8:9]
	s_nop 0
	v_cvt_pk_bf16_f32 v19, v24, v25
	v_cvt_pk_bf16_f32 v20, v20, v21
	v_cvt_pk_bf16_f32 v21, v34, v35
	global_store_dwordx4 v[26:27], v[18:21], off offset:256
	ds_read_b32 v18, v140 offset:704
	s_waitcnt lgkmcnt(0)
	v_pk_mul_f32 v[12:13], v[12:13], v[18:19] op_sel_hi:[1,0]
	s_nop 0
	v_pk_fma_f32 v[8:9], v[30:31], v[12:13], v[8:9]
	v_pk_mul_f32 v[10:11], v[10:11], v[18:19] op_sel_hi:[1,0]
	v_pk_mul_f32 v[12:13], v[14:15], v[18:19] op_sel_hi:[1,0]
	v_pk_mul_f32 v[16:17], v[16:17], v[18:19] op_sel_hi:[1,0]
	v_pk_fma_f32 v[10:11], v[44:45], v[10:11], v[4:5]
	v_pk_fma_f32 v[4:5], v[46:47], v[12:13], v[2:3]
	v_pk_fma_f32 v[6:7], v[32:33], v[16:17], v[6:7]
	s_nop 0
	v_cvt_pk_bf16_f32 v2, v6, v7
	v_cvt_pk_bf16_f32 v3, v8, v9
	v_cvt_pk_bf16_f32 v4, v4, v5
	v_cvt_pk_bf16_f32 v5, v10, v11
	global_store_dwordx4 v[28:29], v[2:5], off offset:256
	s_and_b64 vcc, exec, s[38:39]
	s_mov_b64 s[38:39], -1
	s_cbranch_vccnz .LBB9_1530
